# resume: v49 re-measure after sandbox replacement (same bytes)
# baseline (speedup 1.0000x reference)
; #define PB_BEGIN(bit) unsigned long long pt0_ = 0; if (PROBE_MASK & (1 << (bit))) pt0_ = __builtin_amdgcn_s_memrealtime();
; #define SEAM(k) do { if (IN(k) && IN((k) + 1)) { xcd_barrier(bar); if (PROBE_MASK & (1 << 14)) xcd_barrier(bar); } } while (0)
; #define PHASE_CTX() const Ctx X = mkctx(lds); bf16* const XB = (bf16*)(X.ws + WS_XB); bf16* const Y = (bf16*)(X.ws + WS_Y); bf16* const H = (bf16*)(X.ws + WS_H); float* const ss_mix = (float*)(X.ws + WS_PART); \
;         float* const ss_mix_next = ss_mix; float* const ss_mlp = ss_mix + (size_t)M * 32; (void)XB; (void)Y; (void)H; (void)ss_mix; (void)ss_mix_next; (void)ss_mlp;
; __global__ void __launch_bounds__(NTHR, 2) mega_fwd(Args args) {
;     ...
;         SEAM(pb + 5);
;     ...
;         if (IN(pb + 6)) { PB_BEGIN(7) PHASE_CTX(); pg8::Gemm g{H, (const bf16*)(X.ws + WS_WDN) + (size_t)l * D * FF, M, D, FF}; pg8::StaticOrder S; S.init(M, D, X.G, X.bid);
;             if (l < DEPTH - 1) { pg8::EpiResid<false> E{XB, nullptr, ss_mix_next}; pg8::gemm_phase<pg8::EpiResid<false>, pg8::StaticOrder, true, true>(X.lds, g, S, E); }
;             else { pg8::EpiResid<true> E{XB, X.out(), nullptr}; pg8::gemm_phase<pg8::EpiResid<true>, pg8::StaticOrder, true, true>(X.lds, g, S, E); }
;             PB_END(7) }
;     ...
;         SEAM(pb + 6);
.LBB0_651:
	s_nop 0
	s_nop 0
	s_nop 0
	s_nop 0
	s_nop 0
	s_nop 0
	s_nop 0
	s_nop 0
	s_nop 0
	s_nop 0
	s_nop 0
	s_nop 0
	s_nop 0
	s_nop 0
	s_nop 0
	s_nop 0
	s_nop 0
	s_nop 0
	s_nop 0
	s_nop 0
	s_nop 0
	s_nop 0
	s_nop 0
	s_nop 0
	s_nop 0
	s_nop 0
	s_nop 0
	s_nop 0
	s_nop 0
	s_nop 0
	s_nop 0
	s_nop 0
	s_nop 0
	s_nop 0
	s_nop 0
	s_nop 0
	s_nop 0
	s_nop 0
	s_nop 0
	s_nop 0
	s_nop 0
	s_nop 0
	s_nop 0
	s_nop 0
	s_nop 0
	s_nop 0
	s_nop 0
	s_nop 0
	s_nop 0
	s_nop 0
	s_nop 0
	s_nop 0
	s_nop 0
	s_nop 0
	s_nop 0
	s_nop 0
	s_nop 0
	s_nop 0
	s_nop 0
	s_nop 0
	s_nop 0
	s_nop 0
	s_nop 0
	s_nop 0
	v_readlane_b32 s12, v253, 2
	v_readlane_b32 s14, v253, 4
	v_readlane_b32 s15, v253, 5
	s_cmp_le_i32 s14, s21
	s_cselect_b64 s[0:1], -1, 0
	s_cmp_lt_i32 s21, s15
	s_cselect_b64 s[4:5], -1, 0
	s_and_b64 s[4:5], s[0:1], s[4:5]
	s_mov_b64 s[0:1], -1
	s_and_b64 vcc, exec, s[4:5]
	v_readlane_b32 s13, v253, 3
	s_cbranch_vccnz .LBB0_653
	v_readlane_b32 s0, v252, 30
	s_add_i32 s21, s0, 6
	s_mov_b64 s[0:1], 0
